# attention: union of per-query block masks via one ds_read_b64 per lane + DPP OR-reduction instead of a 64-trip scalar LDS loop
# speedup vs baseline: 1.0070x; 1.0031x over previous
.LBB0_116:
	s_lshl_b64 s[20:21], s[20:21], 1
	v_mov_b32_dpp v42, v42 wave_ror:1 row_mask:0xf bank_mask:0xf
	v_cmp_eq_f32_e64 s[18:19], v42, v39
	v_cmp_gt_f32_e64 s[16:17], v42, v39
	s_and_b64 s[18:19], s[18:19], s[20:21]
	s_or_b64 s[16:17], s[16:17], s[18:19]
	v_addc_co_u32_e64 v41, s[16:17], 0, v41, s[16:17]
	s_lshl_b64 s[20:21], s[20:21], 1
	v_mov_b32_dpp v42, v42 wave_ror:1 row_mask:0xf bank_mask:0xf
	v_cmp_eq_f32_e64 s[18:19], v42, v39
	v_cmp_gt_f32_e64 s[16:17], v42, v39
	s_and_b64 s[18:19], s[18:19], s[20:21]
	s_or_b64 s[16:17], s[16:17], s[18:19]
	v_addc_co_u32_e64 v41, s[16:17], 0, v41, s[16:17]
	s_lshl_b64 s[20:21], s[20:21], 1
	v_mov_b32_dpp v42, v42 wave_ror:1 row_mask:0xf bank_mask:0xf
	v_cmp_eq_f32_e64 s[18:19], v42, v39
	v_cmp_gt_f32_e64 s[16:17], v42, v39
	s_and_b64 s[18:19], s[18:19], s[20:21]
	s_or_b64 s[16:17], s[16:17], s[18:19]
	v_addc_co_u32_e64 v41, s[16:17], 0, v41, s[16:17]
	s_lshl_b64 s[20:21], s[20:21], 1
	v_mov_b32_dpp v42, v42 wave_ror:1 row_mask:0xf bank_mask:0xf
	v_cmp_eq_f32_e64 s[18:19], v42, v39
	v_cmp_gt_f32_e64 s[16:17], v42, v39
	s_and_b64 s[18:19], s[18:19], s[20:21]
	s_or_b64 s[16:17], s[16:17], s[18:19]
	v_addc_co_u32_e64 v41, s[16:17], 0, v41, s[16:17]
	s_lshl_b64 s[20:21], s[20:21], 1
	v_mov_b32_dpp v42, v42 wave_ror:1 row_mask:0xf bank_mask:0xf
	v_cmp_eq_f32_e64 s[18:19], v42, v39
	v_cmp_gt_f32_e64 s[16:17], v42, v39
	s_and_b64 s[18:19], s[18:19], s[20:21]
	s_or_b64 s[16:17], s[16:17], s[18:19]
	v_addc_co_u32_e64 v41, s[16:17], 0, v41, s[16:17]
	s_lshl_b64 s[20:21], s[20:21], 1
	v_mov_b32_dpp v42, v42 wave_ror:1 row_mask:0xf bank_mask:0xf
	v_cmp_eq_f32_e64 s[18:19], v42, v39
	v_cmp_gt_f32_e64 s[16:17], v42, v39
	s_and_b64 s[18:19], s[18:19], s[20:21]
	s_or_b64 s[16:17], s[16:17], s[18:19]
	v_addc_co_u32_e64 v41, s[16:17], 0, v41, s[16:17]
	s_lshl_b64 s[20:21], s[20:21], 1
	v_mov_b32_dpp v42, v42 wave_ror:1 row_mask:0xf bank_mask:0xf
	v_cmp_eq_f32_e64 s[18:19], v42, v39
	v_cmp_gt_f32_e64 s[16:17], v42, v39
	s_and_b64 s[18:19], s[18:19], s[20:21]
	s_or_b64 s[16:17], s[16:17], s[18:19]
	v_addc_co_u32_e64 v41, s[16:17], 0, v41, s[16:17]
	s_add_i32 s5, s5, 1
	s_cmp_eq_u32 s5, 9
	s_cbranch_scc0 .LBB0_116
	s_branch .Lmy_rank_done
	s_nop 0
	s_nop 0
	s_nop 0
	s_nop 0
	s_nop 0
	s_nop 0
	s_nop 0
	s_nop 0
	s_nop 0
	s_nop 0
	s_nop 0
.Lmy_rank_done:
	v_cmp_gt_u32_e64 s[16:17], 16, v41
	s_and_b64 s[16:17], s[16:17], s[14:15]
	s_nop 0
	v_cndmask_b32_e64 v39, 0, 1, s[16:17]
	v_cmp_ne_u32_e64 s[18:19], 0, v39
	s_and_saveexec_b64 s[16:17], vcc
	s_cbranch_execz .LBB0_114
	v_lshl_add_u32 v38, v38, 3, 0
	v_add_u32_e32 v38, 0x21c00, v38
	v_mov_b64_e32 v[40:41], s[18:19]
	ds_write_b64 v38, v[40:41]
	s_branch .LBB0_114
.LBB0_119:
	s_waitcnt lgkmcnt(0)
	s_barrier
	v_lshlrev_b32_e32 v34, 3, v217
	v_add_u32_e32 v34, 0x21c00, v34
	ds_read_b64 v[34:35], v34
	s_waitcnt lgkmcnt(0)
	s_nop 1
	v_or_b32_dpp v34, v34, v34 row_shr:1 row_mask:0xf bank_mask:0xf bound_ctrl:0
	v_or_b32_dpp v35, v35, v35 row_shr:1 row_mask:0xf bank_mask:0xf bound_ctrl:0
	s_nop 1
	v_or_b32_dpp v34, v34, v34 row_shr:2 row_mask:0xf bank_mask:0xf bound_ctrl:0
	v_or_b32_dpp v35, v35, v35 row_shr:2 row_mask:0xf bank_mask:0xf bound_ctrl:0
	s_nop 1
	v_or_b32_dpp v34, v34, v34 row_shr:4 row_mask:0xf bank_mask:0xf bound_ctrl:0
	v_or_b32_dpp v35, v35, v35 row_shr:4 row_mask:0xf bank_mask:0xf bound_ctrl:0
	s_nop 1
	v_or_b32_dpp v34, v34, v34 row_shr:8 row_mask:0xf bank_mask:0xf bound_ctrl:0
	v_or_b32_dpp v35, v35, v35 row_shr:8 row_mask:0xf bank_mask:0xf bound_ctrl:0
	s_nop 1
	v_or_b32_dpp v34, v34, v34 row_bcast:15 row_mask:0xa bank_mask:0xf bound_ctrl:0
	v_or_b32_dpp v35, v35, v35 row_bcast:15 row_mask:0xa bank_mask:0xf bound_ctrl:0
	s_nop 1
	v_or_b32_dpp v34, v34, v34 row_bcast:31 row_mask:0xc bank_mask:0xf bound_ctrl:0
	v_or_b32_dpp v35, v35, v35 row_bcast:31 row_mask:0xc bank_mask:0xf bound_ctrl:0
	s_nop 1
	v_readlane_b32 s14, v34, 63
	v_readlane_b32 s15, v35, 63
	s_branch .Lmy_union_done
.Lmy_union_done:
	s_mul_i32 s5, s24, 0x2800
	v_readlane_b32 s10, v253, 43
	s_mul_hi_i32 s4, s24, 0x2800
	v_readlane_b32 s11, v253, 44
	s_add_u32 s10, s10, s5
	s_addc_u32 s11, s11, s4
	s_lshl_b32 s12, s23, 7
	s_lshl_b32 s13, s23, 8
	s_add_u32 s29, s10, s13
	s_addc_u32 s30, s11, 0
	s_add_u32 s10, s29, 0x1800
	s_addc_u32 s11, s30, 0
	s_lshl_b32 s28, s22, 10
	s_or_b32 s16, s28, s12
	s_ashr_i32 s17, s16, 31
	s_lshl_b64 s[12:13], s[16:17], 13
	v_readlane_b32 s18, v252, 23
	v_readlane_b32 s19, v252, 24
	s_add_u32 s12, s18, s12
	s_addc_u32 s13, s19, s13
	s_add_u32 s18, s14, -1
	s_ff1_i32_b64 s24, s[14:15]
	s_addc_u32 s19, s15, -1
	s_and_b64 s[18:19], s[18:19], s[14:15]
	s_mul_i32 s14, s24, 0xa0000
	s_add_u32 s14, s10, s14
	s_addc_u32 s15, s11, 0
	s_lshl_b32 s17, s24, 7
	s_add_u32 s20, s12, s17
	v_lshlrev_b32_e32 v168, 1, v146
	v_mov_b32_e32 v169, v0
	s_movk_i32 s2, 0x1400
	s_addc_u32 s21, s13, 0
	v_lshl_add_u64 v[34:35], s[14:15], 0, v[168:169]
	v_mad_i64_i32 v[170:171], s[14:15], v154, s2, 0
	v_lshlrev_b32_e32 v172, 1, v164
	v_mov_b32_e32 v173, v0
	v_mad_i64_i32 v[174:175], s[14:15], v152, s2, 0
	v_lshl_add_u64 v[36:37], v[170:171], 1, v[34:35]
	v_lshl_add_u64 v[38:39], s[20:21], 0, v[172:173]
	v_lshlrev_b64 v[166:167], 13, v[142:143]
	v_lshl_add_u64 v[34:35], v[174:175], 1, v[34:35]
	v_lshlrev_b64 v[164:165], 13, v[144:145]
	v_lshl_add_u64 v[40:41], v[38:39], 0, v[166:167]
	global_load_dwordx4 v[98:101], v[36:37], off
	global_load_dwordx4 v[102:105], v[40:41], off
	v_lshl_add_u64 v[36:37], v[38:39], 0, v[164:165]
	global_load_dwordx4 v[106:109], v[34:35], off
	global_load_dwordx4 v[110:113], v[36:37], off
	v_lshl_add_u32 v1, v1, 3, 0
	v_add_u32_e32 v34, 0x21c00, v1
	v_add_u32_e32 v1, 0x21c80, v1
	ds_read_b64 v[180:181], v34
	ds_read_b64 v[182:183], v1
	s_cmp_eq_u64 s[18:19], 0
	v_readlane_b32 s2, v252, 56
	v_lshlrev_b64 v[178:179], 12, v[142:143]
	v_lshlrev_b64 v[176:177], 12, v[144:145]
	s_cselect_b64 s[14:15], -1, 0
	s_cmp_lg_u64 s[18:19], 0
	v_readlane_b32 s3, v252, 57
	s_ff1_i32_b64 s2, s[18:19]
	s_waitcnt lgkmcnt(0)
	s_barrier
	s_waitcnt vmcnt(3)
	ds_write_b128 v155, v[98:101]
	s_waitcnt vmcnt(2)
	ds_write2_b64 v163, v[102:103], v[104:105] offset0:128 offset1:130
	s_waitcnt vmcnt(1)
	ds_write_b128 v153, v[106:109]
	s_waitcnt vmcnt(0)
	ds_write2_b64 v210, v[110:111], v[112:113] offset0:128 offset1:130
	s_cbranch_scc0 .LBB0_123
	s_mul_i32 s17, s2, 0xa0000
	s_add_u32 s20, s10, s17
	s_addc_u32 s21, s11, 0
	s_lshl_b64 s[22:23], s[2:3], 7
	s_add_u32 s22, s12, s22
	s_addc_u32 s23, s13, s23
	v_lshl_add_u64 v[34:35], s[20:21], 0, v[168:169]
	v_lshl_add_u64 v[36:37], v[170:171], 1, v[34:35]
	v_lshl_add_u64 v[38:39], s[22:23], 0, v[172:173]
	v_lshl_add_u64 v[34:35], v[174:175], 1, v[34:35]
	v_lshl_add_u64 v[40:41], v[178:179], 1, v[38:39]
	global_load_dwordx4 v[98:101], v[36:37], off
	global_load_dwordx4 v[102:105], v[40:41], off
	v_lshl_add_u64 v[36:37], v[176:177], 1, v[38:39]
	global_load_dwordx4 v[106:109], v[34:35], off
	global_load_dwordx4 v[110:113], v[36:37], off
